# plus: gated-sum (G4) epilogue issues both gate loads of a row group together
# speedup vs baseline: 1.0039x; 1.0039x over previous
; #define GAS __attribute__((address_space(1)))
; __device__ __forceinline__ float fast_rcp(float x) { return __builtin_amdgcn_rcpf(x); }
; __device__ __forceinline__ v4u tr4(int a, v4u x) { return (v4u){bperm(a, x.x), bperm(a, x.y), bperm(a, x.z), bperm(a, x.w)}; }
;     __device__ __forceinline__ bool operator()(AccT& acc, const Unit& u, int wr, int wc, int fr, int fq) const {
;     ...
;         const int n = u.pm / NPANEL, pm = u.pm - n * NPANEL, pn = u.pn & 3;
;         const int row0 = pm * 256 + wr * 64 + t.tfr, col0 = pn * 256 + wc * 32 + 8 * t.tfq;
; #pragma unroll
;         for (int ai = 0; ai < 2; ++ai)
; #pragma unroll
;             for (int m = 0; m < 4; ++m) { const size_t r = (size_t)(row0 + ai * 128 + m * 16);
; #pragma unroll
;                 for (int bj = 0; bj < 2; ++bj) {
;                     const v4u ga = tr4(t.push, *(const GAS v4u*)(Gt + r * (3 * D) + n * D + col0 + bj * 128));
;                     float f[8] = {bflo(ga.x), bfhi(ga.x), bflo(ga.y), bfhi(ga.y), bflo(ga.z), bfhi(ga.z), bflo(ga.w), bfhi(ga.w)};
;                     if (n < 2) { const v4u gb = tr4(t.push, *(const GAS v4u*)(Gt + r * (3 * D) + (n + 1) * D + col0 + bj * 128));
;                         const float h[8] = {bflo(gb.x), bfhi(gb.x), bflo(gb.y), bfhi(gb.y), bflo(gb.z), bfhi(gb.z), bflo(gb.w), bfhi(gb.w)};
; #pragma unroll
;                         for (int e = 0; e < 8; ++e) f[e] = f[e] * fast_rcp(fmaxf(h[e], 1e-30f)); }
.LBB0_1688:
	s_mul_hi_i32 s13, s8, 0xfe03f81
	s_lshr_b32 s15, s13, 31
	s_ashr_i32 s13, s13, 4
	s_add_i32 s13, s13, s15
	s_mov_b32 s9, s42
	v_mov_b32_e32 v145, v162
	s_mov_b32 s11, s36
	v_mov_b32_e32 v158, v1
	s_mul_i32 s15, s13, 0xfffffefe
	s_add_i32 s15, s15, s8
	s_lshl_b32 s10, s10, 8
	v_lshl_add_u32 v148, v145, 4, v158
	s_lshl_b32 s15, s15, 8
	s_lshl_b32 s11, s11, 6
	s_and_b32 s10, s10, 0x300
	s_lshl_b32 s9, s9, 5
	v_ashrrev_i32_e32 v142, 2, v148
	v_and_b32_e32 v149, 3, v158
	s_add_i32 s9, s9, s10
	s_add_i32 s11, s11, s15
	v_lshl_or_b32 v146, v149, 3, s9
	v_add_u32_e32 v144, s11, v142
	s_lshl_b32 s22, s13, 10
	v_mov_b64_e32 v[142:143], s[86:87]
	s_ashr_i32 s23, s22, 31
	v_ashrrev_i32_e32 v147, 31, v146
	v_mad_i64_i32 v[150:151], s[10:11], v144, s73, v[142:143]
	v_lshl_add_u64 v[152:153], s[22:23], 1, v[150:151]
	v_lshlrev_b64 v[142:143], 1, v[146:147]
	v_lshl_add_u64 v[152:153], v[152:153], 0, v[142:143]
	global_load_dwordx4 v[154:157], v[152:153], off
	v_lshlrev_b32_e32 v158, 4, v158
	v_lshl_add_u32 v165, v145, 2, v158
	s_cmpk_lt_i32 s8, 0x204
	s_cselect_b64 s[10:11], -1, 0
	s_cmpk_gt_i32 s8, 0x203
	s_cselect_b64 s[20:21], -1, 0
	s_add_i32 s24, s22, 0x400
	v_lshl_add_u64 v[150:151], v[150:151], 0, v[142:143]
	s_ashr_i32 s25, s24, 31
	s_and_b64 vcc, exec, s[20:21]
	v_lshl_add_u64 v[150:151], s[24:25], 1, v[150:151]
	s_cbranch_vccnz .Lgate2_skip_0
	global_load_dwordx4 v[166:169], v[150:151], off
.Lgate2_skip_0:
	s_waitcnt vmcnt(0)
	ds_bpermute_b32 v145, v165, v154
	ds_bpermute_b32 v154, v165, v155
	ds_bpermute_b32 v155, v165, v156
	ds_bpermute_b32 v159, v165, v157
	s_waitcnt lgkmcnt(3)
	v_lshlrev_b32_e32 v156, 16, v145
	v_and_b32_e32 v157, 0xffff0000, v145
	s_waitcnt lgkmcnt(2)
	v_lshlrev_b32_e32 v160, 16, v154
	v_and_b32_e32 v161, 0xffff0000, v154
	s_waitcnt lgkmcnt(1)
	v_lshlrev_b32_e32 v154, 16, v155
	v_and_b32_e32 v155, 0xffff0000, v155
	s_waitcnt lgkmcnt(0)
	v_lshlrev_b32_e32 v158, 16, v159
	v_and_b32_e32 v159, 0xffff0000, v159
	s_cbranch_vccnz .LBB0_1690
	s_waitcnt vmcnt(0)
	ds_bpermute_b32 v145, v165, v166
	ds_bpermute_b32 v166, v165, v167
	ds_bpermute_b32 v167, v165, v168
	ds_bpermute_b32 v168, v165, v169
	s_waitcnt lgkmcnt(3)
	v_lshlrev_b32_e32 v169, 16, v145
	v_and_b32_e32 v145, 0xffff0000, v145
	s_waitcnt lgkmcnt(2)
	v_lshlrev_b32_e32 v170, 16, v166
	v_and_b32_e32 v166, 0xffff0000, v166
	s_waitcnt lgkmcnt(1)
	v_lshlrev_b32_e32 v171, 16, v167
	v_and_b32_e32 v167, 0xffff0000, v167
	s_waitcnt lgkmcnt(0)
	v_lshlrev_b32_e32 v172, 16, v168
	v_and_b32_e32 v168, 0xffff0000, v168
	v_max_f32_e32 v169, v169, v169
	v_max_f32_e32 v145, v145, v145
	v_max_f32_e32 v170, v170, v170
	v_max_f32_e32 v166, v166, v166
	v_max_f32_e32 v171, v171, v171
	v_max_f32_e32 v167, v167, v167
	v_max_f32_e32 v172, v172, v172
	v_max_f32_e32 v168, v168, v168
	v_max_f32_e32 v169, 0xda24260, v169
	v_max_f32_e32 v145, 0xda24260, v145
	v_max_f32_e32 v170, 0xda24260, v170
	v_max_f32_e32 v174, 0xda24260, v166
	v_max_f32_e32 v171, 0xda24260, v171
	v_max_f32_e32 v167, 0xda24260, v167
	v_max_f32_e32 v172, 0xda24260, v172
	v_max_f32_e32 v173, 0xda24260, v168
	v_rcp_f32_e32 v166, v169
	v_rcp_f32_e32 v168, v170
	v_rcp_f32_e32 v170, v171
	v_rcp_f32_e32 v172, v172
	v_rcp_f32_e32 v173, v173
	v_rcp_f32_e32 v171, v167
	v_rcp_f32_e32 v169, v174
	v_rcp_f32_e32 v167, v145
	v_pk_mul_f32 v[158:159], v[172:173], v[158:159]
	v_pk_mul_f32 v[154:155], v[170:171], v[154:155]
	v_pk_mul_f32 v[160:161], v[168:169], v[160:161]
	v_pk_mul_f32 v[156:157], v[166:167], v[156:157]

; #define GAS __attribute__((address_space(1)))
; __device__ __forceinline__ float fast_rcp(float x) { return __builtin_amdgcn_rcpf(x); }
; __device__ __forceinline__ v4u tr4(int a, v4u x) { return (v4u){bperm(a, x.x), bperm(a, x.y), bperm(a, x.z), bperm(a, x.w)}; }
;     __device__ __forceinline__ bool operator()(AccT& acc, const Unit& u, int wr, int wc, int fr, int fq) const {
;     ...
;             for (int m = 0; m < 4; ++m) { const size_t r = (size_t)(row0 + ai * 128 + m * 16);
; #pragma unroll
;                 for (int bj = 0; bj < 2; ++bj) {
;                     const v4u ga = tr4(t.push, *(const GAS v4u*)(Gt + r * (3 * D) + n * D + col0 + bj * 128));
;                     float f[8] = {bflo(ga.x), bfhi(ga.x), bflo(ga.y), bfhi(ga.y), bflo(ga.z), bfhi(ga.z), bflo(ga.w), bfhi(ga.w)};
;                     if (n < 2) { const v4u gb = tr4(t.push, *(const GAS v4u*)(Gt + r * (3 * D) + (n + 1) * D + col0 + bj * 128));
;                         const float h[8] = {bflo(gb.x), bfhi(gb.x), bflo(gb.y), bfhi(gb.y), bflo(gb.z), bfhi(gb.z), bflo(gb.w), bfhi(gb.w)};
; #pragma unroll
;                         for (int e = 0; e < 8; ++e) f[e] = f[e] * fast_rcp(fmaxf(h[e], 1e-30f)); }
.LBB0_1692:
	global_load_dwordx4 v[152:155], v[152:153], off offset:256
	v_cndmask_b32_e64 v145, 0, 1, s[10:11]
	v_cmp_ne_u32_e64 s[8:9], 1, v145
	s_andn2_b64 vcc, exec, s[10:11]
	s_cbranch_vccnz .Lgate2_skip_2
	global_load_dwordx4 v[168:171], v[150:151], off offset:256
.Lgate2_skip_2:
	s_waitcnt vmcnt(0)
	ds_bpermute_b32 v145, v165, v152
	ds_bpermute_b32 v152, v165, v153
	ds_bpermute_b32 v153, v165, v154
	ds_bpermute_b32 v157, v165, v155
	s_waitcnt lgkmcnt(3)
	v_lshlrev_b32_e32 v154, 16, v145
	v_and_b32_e32 v155, 0xffff0000, v145
	s_waitcnt lgkmcnt(2)
	v_lshlrev_b32_e32 v158, 16, v152
	v_and_b32_e32 v159, 0xffff0000, v152
	s_waitcnt lgkmcnt(1)
	v_lshlrev_b32_e32 v152, 16, v153
	v_and_b32_e32 v153, 0xffff0000, v153
	s_waitcnt lgkmcnt(0)
	v_lshlrev_b32_e32 v156, 16, v157
	v_and_b32_e32 v157, 0xffff0000, v157
	s_cbranch_vccnz .LBB0_1694
	s_waitcnt vmcnt(0)
	ds_bpermute_b32 v145, v165, v168
	ds_bpermute_b32 v150, v165, v169
	ds_bpermute_b32 v151, v165, v170
	ds_bpermute_b32 v160, v165, v171
	s_waitcnt lgkmcnt(3)
	v_lshlrev_b32_e32 v161, 16, v145
	v_and_b32_e32 v145, 0xffff0000, v145
	s_waitcnt lgkmcnt(2)
	v_lshlrev_b32_e32 v167, 16, v150
	v_and_b32_e32 v150, 0xffff0000, v150
	s_waitcnt lgkmcnt(1)
	v_lshlrev_b32_e32 v168, 16, v151
	v_and_b32_e32 v151, 0xffff0000, v151
	s_waitcnt lgkmcnt(0)
	v_lshlrev_b32_e32 v169, 16, v160
	v_and_b32_e32 v160, 0xffff0000, v160
	v_max_f32_e32 v161, v161, v161
	v_max_f32_e32 v145, v145, v145
	v_max_f32_e32 v167, v167, v167
	v_max_f32_e32 v150, v150, v150
	v_max_f32_e32 v168, v168, v168
	v_max_f32_e32 v151, v151, v151
	v_max_f32_e32 v169, v169, v169
	v_max_f32_e32 v160, v160, v160
	v_max_f32_e32 v161, 0xda24260, v161
	v_max_f32_e32 v145, 0xda24260, v145
	v_max_f32_e32 v167, 0xda24260, v167
	v_max_f32_e32 v172, 0xda24260, v150
	v_max_f32_e32 v168, 0xda24260, v168
	v_max_f32_e32 v151, 0xda24260, v151
	v_max_f32_e32 v169, 0xda24260, v169
	v_max_f32_e32 v171, 0xda24260, v160
	v_rcp_f32_e32 v150, v161
	v_rcp_f32_e32 v160, v167
	v_rcp_f32_e32 v168, v168
	v_rcp_f32_e32 v170, v169
	v_rcp_f32_e32 v171, v171
	v_rcp_f32_e32 v169, v151
	v_rcp_f32_e32 v161, v172
	v_rcp_f32_e32 v151, v145
	v_pk_mul_f32 v[156:157], v[170:171], v[156:157]
	v_pk_mul_f32 v[152:153], v[168:169], v[152:153]
	v_pk_mul_f32 v[158:159], v[160:161], v[158:159]
	v_pk_mul_f32 v[154:155], v[150:151], v[154:155]

; #define GAS __attribute__((address_space(1)))
; __device__ __forceinline__ float fast_rcp(float x) { return __builtin_amdgcn_rcpf(x); }
; __device__ __forceinline__ v4u tr4(int a, v4u x) { return (v4u){bperm(a, x.x), bperm(a, x.y), bperm(a, x.z), bperm(a, x.w)}; }
;     __device__ __forceinline__ bool operator()(AccT& acc, const Unit& u, int wr, int wc, int fr, int fq) const {
;     ...
;             for (int m = 0; m < 4; ++m) { const size_t r = (size_t)(row0 + ai * 128 + m * 16);
; #pragma unroll
;                 for (int bj = 0; bj < 2; ++bj) {
;                     const v4u ga = tr4(t.push, *(const GAS v4u*)(Gt + r * (3 * D) + n * D + col0 + bj * 128));
;                     float f[8] = {bflo(ga.x), bfhi(ga.x), bflo(ga.y), bfhi(ga.y), bflo(ga.z), bfhi(ga.z), bflo(ga.w), bfhi(ga.w)};
;                     if (n < 2) { const v4u gb = tr4(t.push, *(const GAS v4u*)(Gt + r * (3 * D) + (n + 1) * D + col0 + bj * 128));
;                         const float h[8] = {bflo(gb.x), bfhi(gb.x), bflo(gb.y), bfhi(gb.y), bflo(gb.z), bfhi(gb.z), bflo(gb.w), bfhi(gb.w)};
; #pragma unroll
;                         for (int e = 0; e < 8; ++e) f[e] = f[e] * fast_rcp(fmaxf(h[e], 1e-30f)); }
.LBB0_1696:
	v_add_u32_e32 v148, 16, v144
	s_nop 0
	v_mov_b64_e32 v[150:151], s[86:87]
	v_mad_i64_i32 v[150:151], s[26:27], v148, s73, v[150:151]
	v_lshl_add_u64 v[152:153], s[22:23], 1, v[150:151]
	v_lshl_add_u64 v[152:153], v[152:153], 0, v[142:143]
	global_load_dwordx4 v[154:157], v[152:153], off
	v_lshl_add_u64 v[150:151], v[150:151], 0, v[142:143]
	s_and_b64 vcc, exec, s[8:9]
	v_lshl_add_u64 v[150:151], s[24:25], 1, v[150:151]
	s_cbranch_vccnz .Lgate2_skip_4
	global_load_dwordx4 v[168:171], v[150:151], off
.Lgate2_skip_4:
	s_waitcnt vmcnt(0)
	ds_bpermute_b32 v145, v165, v154
	ds_bpermute_b32 v149, v165, v155
	ds_bpermute_b32 v155, v165, v156
	ds_bpermute_b32 v159, v165, v157
	s_waitcnt lgkmcnt(3)
	v_lshlrev_b32_e32 v156, 16, v145
	v_and_b32_e32 v157, 0xffff0000, v145
	s_waitcnt lgkmcnt(2)
	v_lshlrev_b32_e32 v160, 16, v149
	v_and_b32_e32 v161, 0xffff0000, v149
	s_waitcnt lgkmcnt(1)
	v_lshlrev_b32_e32 v154, 16, v155
	v_and_b32_e32 v155, 0xffff0000, v155
	s_waitcnt lgkmcnt(0)
	v_lshlrev_b32_e32 v158, 16, v159
	v_and_b32_e32 v159, 0xffff0000, v159
	s_cbranch_vccnz .LBB0_1698
	s_waitcnt vmcnt(0)
	ds_bpermute_b32 v145, v165, v168
	ds_bpermute_b32 v149, v165, v169
	ds_bpermute_b32 v167, v165, v170
	ds_bpermute_b32 v168, v165, v171
	s_waitcnt lgkmcnt(3)
	v_lshlrev_b32_e32 v169, 16, v145
	v_and_b32_e32 v145, 0xffff0000, v145
	s_waitcnt lgkmcnt(2)
	v_lshlrev_b32_e32 v170, 16, v149
	v_and_b32_e32 v149, 0xffff0000, v149
	s_waitcnt lgkmcnt(1)
	v_lshlrev_b32_e32 v171, 16, v167
	v_and_b32_e32 v167, 0xffff0000, v167
	s_waitcnt lgkmcnt(0)
	v_lshlrev_b32_e32 v172, 16, v168
	v_and_b32_e32 v168, 0xffff0000, v168
	v_max_f32_e32 v169, v169, v169
	v_max_f32_e32 v145, v145, v145
	v_max_f32_e32 v170, v170, v170
	v_max_f32_e32 v149, v149, v149
	v_max_f32_e32 v171, v171, v171
	v_max_f32_e32 v167, v167, v167
	v_max_f32_e32 v172, v172, v172
	v_max_f32_e32 v168, v168, v168
	v_max_f32_e32 v169, 0xda24260, v169
	v_max_f32_e32 v145, 0xda24260, v145
	v_max_f32_e32 v170, 0xda24260, v170
	v_max_f32_e32 v149, 0xda24260, v149
	v_max_f32_e32 v171, 0xda24260, v171
	v_max_f32_e32 v167, 0xda24260, v167
	v_max_f32_e32 v173, 0xda24260, v172
	v_max_f32_e32 v175, 0xda24260, v168
	v_rcp_f32_e32 v168, v169
	v_rcp_f32_e32 v170, v170
	v_rcp_f32_e32 v172, v171
	v_rcp_f32_e32 v174, v173
	v_rcp_f32_e32 v175, v175
	v_rcp_f32_e32 v173, v167
	v_rcp_f32_e32 v171, v149
	v_rcp_f32_e32 v169, v145
	v_pk_mul_f32 v[158:159], v[174:175], v[158:159]
	v_pk_mul_f32 v[154:155], v[172:173], v[154:155]
	v_pk_mul_f32 v[160:161], v[170:171], v[160:161]
	v_pk_mul_f32 v[156:157], v[168:169], v[156:157]

; #define GAS __attribute__((address_space(1)))
; __device__ __forceinline__ v4u tr4(int a, v4u x) { return (v4u){bperm(a, x.x), bperm(a, x.y), bperm(a, x.z), bperm(a, x.w)}; }
;     __device__ __forceinline__ bool operator()(AccT& acc, const Unit& u, int wr, int wc, int fr, int fq) const {
;     ...
;             for (int m = 0; m < 4; ++m) { const size_t r = (size_t)(row0 + ai * 128 + m * 16);
; #pragma unroll
;                 for (int bj = 0; bj < 2; ++bj) {
;                     const v4u ga = tr4(t.push, *(const GAS v4u*)(Gt + r * (3 * D) + n * D + col0 + bj * 128));
;                     float f[8] = {bflo(ga.x), bfhi(ga.x), bflo(ga.y), bfhi(ga.y), bflo(ga.z), bfhi(ga.z), bflo(ga.w), bfhi(ga.w)};
;                     if (n < 2) { const v4u gb = tr4(t.push, *(const GAS v4u*)(Gt + r * (3 * D) + (n + 1) * D + col0 + bj * 128));
.LBB0_1700:
	global_load_dwordx4 v[152:155], v[152:153], off offset:256
	s_and_b64 vcc, exec, s[8:9]
	s_cbranch_vccnz .Lgate2_skip_6
	global_load_dwordx4 v[168:171], v[150:151], off offset:256

; #define GAS __attribute__((address_space(1)))
; __device__ __forceinline__ v4u tr4(int a, v4u x) { return (v4u){bperm(a, x.x), bperm(a, x.y), bperm(a, x.z), bperm(a, x.w)}; }
;     __device__ __forceinline__ bool operator()(AccT& acc, const Unit& u, int wr, int wc, int fr, int fq) const {
;     ...
;             for (int m = 0; m < 4; ++m) { const size_t r = (size_t)(row0 + ai * 128 + m * 16);
; #pragma unroll
;                 for (int bj = 0; bj < 2; ++bj) {
;                     const v4u ga = tr4(t.push, *(const GAS v4u*)(Gt + r * (3 * D) + n * D + col0 + bj * 128));
;                     float f[8] = {bflo(ga.x), bfhi(ga.x), bflo(ga.y), bfhi(ga.y), bflo(ga.z), bfhi(ga.z), bflo(ga.w), bfhi(ga.w)};
;                     if (n < 2) { const v4u gb = tr4(t.push, *(const GAS v4u*)(Gt + r * (3 * D) + (n + 1) * D + col0 + bj * 128));
.LBB0_1704:
	v_add_u32_e32 v148, 32, v144
	s_nop 0
	v_mov_b64_e32 v[150:151], s[86:87]
	v_mad_i64_i32 v[150:151], s[26:27], v148, s73, v[150:151]
	v_lshl_add_u64 v[152:153], s[22:23], 1, v[150:151]
	v_lshl_add_u64 v[152:153], v[152:153], 0, v[142:143]
	global_load_dwordx4 v[154:157], v[152:153], off
	v_lshl_add_u64 v[150:151], v[150:151], 0, v[142:143]
	s_and_b64 vcc, exec, s[8:9]
	v_lshl_add_u64 v[150:151], s[24:25], 1, v[150:151]
	s_cbranch_vccnz .Lgate2_skip_8
	global_load_dwordx4 v[168:171], v[150:151], off

; #define GAS __attribute__((address_space(1)))
; __device__ __forceinline__ v4u tr4(int a, v4u x) { return (v4u){bperm(a, x.x), bperm(a, x.y), bperm(a, x.z), bperm(a, x.w)}; }
;     __device__ __forceinline__ bool operator()(AccT& acc, const Unit& u, int wr, int wc, int fr, int fq) const {
;     ...
;             for (int m = 0; m < 4; ++m) { const size_t r = (size_t)(row0 + ai * 128 + m * 16);
; #pragma unroll
;                 for (int bj = 0; bj < 2; ++bj) {
;                     const v4u ga = tr4(t.push, *(const GAS v4u*)(Gt + r * (3 * D) + n * D + col0 + bj * 128));
;                     float f[8] = {bflo(ga.x), bfhi(ga.x), bflo(ga.y), bfhi(ga.y), bflo(ga.z), bfhi(ga.z), bflo(ga.w), bfhi(ga.w)};
;                     if (n < 2) { const v4u gb = tr4(t.push, *(const GAS v4u*)(Gt + r * (3 * D) + (n + 1) * D + col0 + bj * 128));
.LBB0_1712:
	v_add_u32_e32 v148, 48, v144
	s_nop 0
	v_mov_b64_e32 v[150:151], s[86:87]
	v_mad_i64_i32 v[150:151], s[26:27], v148, s73, v[150:151]
	v_lshl_add_u64 v[152:153], s[22:23], 1, v[150:151]
	v_lshl_add_u64 v[152:153], v[152:153], 0, v[142:143]
	global_load_dwordx4 v[154:157], v[152:153], off
	v_lshl_add_u64 v[150:151], v[150:151], 0, v[142:143]
	s_and_b64 vcc, exec, s[8:9]
	v_lshl_add_u64 v[150:151], s[24:25], 1, v[150:151]
	s_cbranch_vccnz .Lgate2_skip_12
	global_load_dwordx4 v[168:171], v[150:151], off

; #define GAS __attribute__((address_space(1)))
; __device__ __forceinline__ v4u tr4(int a, v4u x) { return (v4u){bperm(a, x.x), bperm(a, x.y), bperm(a, x.z), bperm(a, x.w)}; }
;     __device__ __forceinline__ bool operator()(AccT& acc, const Unit& u, int wr, int wc, int fr, int fq) const {
;     ...
;             for (int m = 0; m < 4; ++m) { const size_t r = (size_t)(row0 + ai * 128 + m * 16);
; #pragma unroll
;                 for (int bj = 0; bj < 2; ++bj) {
;                     const v4u ga = tr4(t.push, *(const GAS v4u*)(Gt + r * (3 * D) + n * D + col0 + bj * 128));
;                     float f[8] = {bflo(ga.x), bfhi(ga.x), bflo(ga.y), bfhi(ga.y), bflo(ga.z), bfhi(ga.z), bflo(ga.w), bfhi(ga.w)};
;                     if (n < 2) { const v4u gb = tr4(t.push, *(const GAS v4u*)(Gt + r * (3 * D) + (n + 1) * D + col0 + bj * 128));
.LBB0_1720:
	v_add_u32_e32 v148, 0x80, v144
	s_nop 0
	v_mov_b64_e32 v[150:151], s[86:87]
	v_mad_i64_i32 v[150:151], s[26:27], v148, s73, v[150:151]
	v_lshl_add_u64 v[152:153], s[22:23], 1, v[150:151]
	v_lshl_add_u64 v[152:153], v[152:153], 0, v[142:143]
	global_load_dwordx4 v[154:157], v[152:153], off
	v_lshl_add_u64 v[150:151], v[150:151], 0, v[142:143]
	s_and_b64 vcc, exec, s[8:9]
	v_lshl_add_u64 v[150:151], s[24:25], 1, v[150:151]
	s_cbranch_vccnz .Lgate2_skip_16
	global_load_dwordx4 v[168:171], v[150:151], off

; #define GAS __attribute__((address_space(1)))
; __device__ __forceinline__ v4u tr4(int a, v4u x) { return (v4u){bperm(a, x.x), bperm(a, x.y), bperm(a, x.z), bperm(a, x.w)}; }
;     __device__ __forceinline__ bool operator()(AccT& acc, const Unit& u, int wr, int wc, int fr, int fq) const {
;     ...
;             for (int m = 0; m < 4; ++m) { const size_t r = (size_t)(row0 + ai * 128 + m * 16);
; #pragma unroll
;                 for (int bj = 0; bj < 2; ++bj) {
;                     const v4u ga = tr4(t.push, *(const GAS v4u*)(Gt + r * (3 * D) + n * D + col0 + bj * 128));
;                     float f[8] = {bflo(ga.x), bfhi(ga.x), bflo(ga.y), bfhi(ga.y), bflo(ga.z), bfhi(ga.z), bflo(ga.w), bfhi(ga.w)};
;                     if (n < 2) { const v4u gb = tr4(t.push, *(const GAS v4u*)(Gt + r * (3 * D) + (n + 1) * D + col0 + bj * 128));
.LBB0_1728:
	v_add_u32_e32 v148, 0x90, v144
	s_nop 0
	v_mov_b64_e32 v[150:151], s[86:87]
	v_mad_i64_i32 v[150:151], s[26:27], v148, s73, v[150:151]
	v_lshl_add_u64 v[152:153], s[22:23], 1, v[150:151]
	v_lshl_add_u64 v[152:153], v[152:153], 0, v[142:143]
	global_load_dwordx4 v[154:157], v[152:153], off
	v_lshl_add_u64 v[150:151], v[150:151], 0, v[142:143]
	s_and_b64 vcc, exec, s[8:9]
	v_lshl_add_u64 v[150:151], s[24:25], 1, v[150:151]
	s_cbranch_vccnz .Lgate2_skip_20
	global_load_dwordx4 v[168:171], v[150:151], off

; #define GAS __attribute__((address_space(1)))
; __device__ __forceinline__ v4u tr4(int a, v4u x) { return (v4u){bperm(a, x.x), bperm(a, x.y), bperm(a, x.z), bperm(a, x.w)}; }
;     __device__ __forceinline__ bool operator()(AccT& acc, const Unit& u, int wr, int wc, int fr, int fq) const {
;     ...
;             for (int m = 0; m < 4; ++m) { const size_t r = (size_t)(row0 + ai * 128 + m * 16);
; #pragma unroll
;                 for (int bj = 0; bj < 2; ++bj) {
;                     const v4u ga = tr4(t.push, *(const GAS v4u*)(Gt + r * (3 * D) + n * D + col0 + bj * 128));
;                     float f[8] = {bflo(ga.x), bfhi(ga.x), bflo(ga.y), bfhi(ga.y), bflo(ga.z), bfhi(ga.z), bflo(ga.w), bfhi(ga.w)};
;                     if (n < 2) { const v4u gb = tr4(t.push, *(const GAS v4u*)(Gt + r * (3 * D) + (n + 1) * D + col0 + bj * 128));
.LBB0_1736:
	v_add_u32_e32 v148, 0xa0, v144
	s_nop 0
	v_mov_b64_e32 v[150:151], s[86:87]
	v_mad_i64_i32 v[150:151], s[26:27], v148, s73, v[150:151]
	v_lshl_add_u64 v[152:153], s[22:23], 1, v[150:151]
	v_lshl_add_u64 v[152:153], v[152:153], 0, v[142:143]
	global_load_dwordx4 v[154:157], v[152:153], off
	v_lshl_add_u64 v[150:151], v[150:151], 0, v[142:143]
	s_and_b64 vcc, exec, s[8:9]
	v_lshl_add_u64 v[150:151], s[24:25], 1, v[150:151]
	s_cbranch_vccnz .Lgate2_skip_24
	global_load_dwordx4 v[168:171], v[150:151], off

; #define GAS __attribute__((address_space(1)))
; __device__ __forceinline__ float fast_rcp(float x) { return __builtin_amdgcn_rcpf(x); }
; __device__ __forceinline__ v4u tr4(int a, v4u x) { return (v4u){bperm(a, x.x), bperm(a, x.y), bperm(a, x.z), bperm(a, x.w)}; }
;     __device__ __forceinline__ bool operator()(AccT& acc, const Unit& u, int wr, int wc, int fr, int fq) const {
;     ...
;             for (int m = 0; m < 4; ++m) { const size_t r = (size_t)(row0 + ai * 128 + m * 16);
; #pragma unroll
;                 for (int bj = 0; bj < 2; ++bj) {
;                     const v4u ga = tr4(t.push, *(const GAS v4u*)(Gt + r * (3 * D) + n * D + col0 + bj * 128));
;                     float f[8] = {bflo(ga.x), bfhi(ga.x), bflo(ga.y), bfhi(ga.y), bflo(ga.z), bfhi(ga.z), bflo(ga.w), bfhi(ga.w)};
;                     if (n < 2) { const v4u gb = tr4(t.push, *(const GAS v4u*)(Gt + r * (3 * D) + (n + 1) * D + col0 + bj * 128));
;                         const float h[8] = {bflo(gb.x), bfhi(gb.x), bflo(gb.y), bfhi(gb.y), bflo(gb.z), bfhi(gb.z), bflo(gb.w), bfhi(gb.w)};
; #pragma unroll
;                         for (int e = 0; e < 8; ++e) f[e] = f[e] * fast_rcp(fmaxf(h[e], 1e-30f)); }
.LBB0_1744:
	s_nop 1
	v_add_u32_e32 v150, 0xb0, v144
	v_mov_b64_e32 v[144:145], s[86:87]
	v_mad_i64_i32 v[144:145], s[26:27], v150, s73, v[144:145]
	v_lshl_add_u64 v[148:149], s[22:23], 1, v[144:145]
	v_lshl_add_u64 v[148:149], v[148:149], 0, v[142:143]
	global_load_dwordx4 v[152:155], v[148:149], off
	v_lshl_add_u64 v[142:143], v[144:145], 0, v[142:143]
	v_lshl_add_u64 v[144:145], s[24:25], 1, v[142:143]
	s_and_b64 vcc, exec, s[8:9]
	s_cbranch_vccnz .Lgate2_skip_28
	global_load_dwordx4 v[168:171], v[144:145], off
.Lgate2_skip_28:
	s_waitcnt vmcnt(0)
	ds_bpermute_b32 v151, v165, v152
	ds_bpermute_b32 v142, v165, v153
	ds_bpermute_b32 v143, v165, v154
	ds_bpermute_b32 v157, v165, v155
	s_waitcnt lgkmcnt(3)
	v_lshlrev_b32_e32 v154, 16, v151
	v_and_b32_e32 v155, 0xffff0000, v151
	s_waitcnt lgkmcnt(2)
	v_lshlrev_b32_e32 v158, 16, v142
	v_and_b32_e32 v159, 0xffff0000, v142
	s_waitcnt lgkmcnt(1)
	v_lshlrev_b32_e32 v152, 16, v143
	v_and_b32_e32 v153, 0xffff0000, v143
	s_waitcnt lgkmcnt(0)
	v_lshlrev_b32_e32 v156, 16, v157
	v_and_b32_e32 v157, 0xffff0000, v157
	s_cbranch_vccnz .LBB0_1746
	s_waitcnt vmcnt(0)
	ds_bpermute_b32 v142, v165, v168
	ds_bpermute_b32 v143, v165, v169
	ds_bpermute_b32 v151, v165, v170
	ds_bpermute_b32 v160, v165, v171
	s_waitcnt lgkmcnt(3)
	v_lshlrev_b32_e32 v161, 16, v142
	v_and_b32_e32 v142, 0xffff0000, v142
	s_waitcnt lgkmcnt(2)
	v_lshlrev_b32_e32 v167, 16, v143
	v_and_b32_e32 v143, 0xffff0000, v143
	s_waitcnt lgkmcnt(1)
	v_lshlrev_b32_e32 v168, 16, v151
	v_and_b32_e32 v151, 0xffff0000, v151
	s_waitcnt lgkmcnt(0)
	v_lshlrev_b32_e32 v169, 16, v160
	v_and_b32_e32 v160, 0xffff0000, v160
	v_max_f32_e32 v161, v161, v161
	v_max_f32_e32 v142, v142, v142
	v_max_f32_e32 v167, v167, v167
	v_max_f32_e32 v143, v143, v143
	v_max_f32_e32 v168, v168, v168
	v_max_f32_e32 v151, v151, v151
	v_max_f32_e32 v169, v169, v169
	v_max_f32_e32 v160, v160, v160
	v_max_f32_e32 v161, 0xda24260, v161
	v_max_f32_e32 v172, 0xda24260, v142
	v_max_f32_e32 v167, 0xda24260, v167
	v_max_f32_e32 v143, 0xda24260, v143
	v_max_f32_e32 v168, 0xda24260, v168
	v_max_f32_e32 v151, 0xda24260, v151
	v_max_f32_e32 v169, 0xda24260, v169
	v_max_f32_e32 v171, 0xda24260, v160
	v_rcp_f32_e32 v142, v161
	v_rcp_f32_e32 v160, v167
	v_rcp_f32_e32 v168, v168
	v_rcp_f32_e32 v170, v169
	v_rcp_f32_e32 v171, v171
	v_rcp_f32_e32 v169, v151
	v_rcp_f32_e32 v161, v143
	v_rcp_f32_e32 v143, v172
	v_pk_mul_f32 v[156:157], v[170:171], v[156:157]
	v_pk_mul_f32 v[152:153], v[168:169], v[152:153]
	v_pk_mul_f32 v[158:159], v[160:161], v[158:159]
	v_pk_mul_f32 v[154:155], v[142:143], v[154:155]

; #define GAS __attribute__((address_space(1)))
; __device__ __forceinline__ float fast_rcp(float x) { return __builtin_amdgcn_rcpf(x); }
; __device__ __forceinline__ v4u tr4(int a, v4u x) { return (v4u){bperm(a, x.x), bperm(a, x.y), bperm(a, x.z), bperm(a, x.w)}; }
; __device__ __forceinline__ v4u pack8(const f32x4& a, const f32x4& b) { return (v4u){pg8::cvt_pk_bf16(a[0], a[1]), pg8::cvt_pk_bf16(a[2], a[3]), pg8::cvt_pk_bf16(b[0], b[1]), pg8::cvt_pk_bf16(b[2], b[3])}; }
;     __device__ __forceinline__ bool operator()(AccT& acc, const Unit& u, int wr, int wc, int fr, int fq) const {
;     ...
;             for (int m = 0; m < 4; ++m) { const size_t r = (size_t)(row0 + ai * 128 + m * 16);
; #pragma unroll
;                 for (int bj = 0; bj < 2; ++bj) {
;                     const v4u ga = tr4(t.push, *(const GAS v4u*)(Gt + r * (3 * D) + n * D + col0 + bj * 128));
;                     float f[8] = {bflo(ga.x), bfhi(ga.x), bflo(ga.y), bfhi(ga.y), bflo(ga.z), bfhi(ga.z), bflo(ga.w), bfhi(ga.w)};
;                     if (n < 2) { const v4u gb = tr4(t.push, *(const GAS v4u*)(Gt + r * (3 * D) + (n + 1) * D + col0 + bj * 128));
;                         const float h[8] = {bflo(gb.x), bfhi(gb.x), bflo(gb.y), bfhi(gb.y), bflo(gb.z), bfhi(gb.z), bflo(gb.w), bfhi(gb.w)};
; #pragma unroll
;                         for (int e = 0; e < 8; ++e) f[e] = f[e] * fast_rcp(fmaxf(h[e], 1e-30f)); }
;                     f32x4 v0 = acc[ai][bj][m][0], v1 = acc[ai][bj][m][1];
;                     v0 = v0 * (f32x4){f[0], f[1], f[2], f[3]}; v1 = v1 * (f32x4){f[4], f[5], f[6], f[7]};
;                     acc[ai][bj][m][0] = v0; acc[ai][bj][m][1] = v1;
;                     if (n == 2) *(GAS v4u*)(mix + r * D + col0 + bj * 128) = tr4(t.pull, pack8(v0, v1));
.LBB0_1748:
	global_load_dwordx4 v[146:149], v[148:149], off offset:256
	s_and_b64 vcc, exec, s[8:9]
	s_cbranch_vccnz .Lgate2_skip_30
	global_load_dwordx4 v[154:157], v[144:145], off offset:256
.Lgate2_skip_30:
	s_waitcnt vmcnt(0)
	ds_bpermute_b32 v146, v165, v146
	ds_bpermute_b32 v147, v165, v147
	ds_bpermute_b32 v150, v165, v148
	ds_bpermute_b32 v151, v165, v149
	s_waitcnt lgkmcnt(3)
	v_lshlrev_b32_e32 v148, 16, v146
	v_and_b32_e32 v149, 0xffff0000, v146
	s_waitcnt lgkmcnt(2)
	v_lshlrev_b32_e32 v152, 16, v147
	v_and_b32_e32 v153, 0xffff0000, v147
	s_waitcnt lgkmcnt(1)
	v_lshlrev_b32_e32 v146, 16, v150
	v_and_b32_e32 v147, 0xffff0000, v150
	s_waitcnt lgkmcnt(0)
	v_lshlrev_b32_e32 v150, 16, v151
	v_and_b32_e32 v151, 0xffff0000, v151
	s_cbranch_vccnz .LBB0_1750
	s_waitcnt vmcnt(0)
	ds_bpermute_b32 v144, v165, v154
	ds_bpermute_b32 v145, v165, v155
	ds_bpermute_b32 v154, v165, v156
	ds_bpermute_b32 v155, v165, v157
	s_waitcnt lgkmcnt(3)
	v_lshlrev_b32_e32 v156, 16, v144
	v_and_b32_e32 v144, 0xffff0000, v144
	s_waitcnt lgkmcnt(2)
	v_lshlrev_b32_e32 v157, 16, v145
	v_and_b32_e32 v145, 0xffff0000, v145
	s_waitcnt lgkmcnt(1)
	v_lshlrev_b32_e32 v158, 16, v154
	v_and_b32_e32 v154, 0xffff0000, v154
	s_waitcnt lgkmcnt(0)
	v_lshlrev_b32_e32 v159, 16, v155
	v_and_b32_e32 v155, 0xffff0000, v155
	v_max_f32_e32 v156, v156, v156
	v_max_f32_e32 v144, v144, v144
	v_max_f32_e32 v157, v157, v157
	v_max_f32_e32 v145, v145, v145
	v_max_f32_e32 v158, v158, v158
	v_max_f32_e32 v154, v154, v154
	v_max_f32_e32 v159, v159, v159
	v_max_f32_e32 v155, v155, v155
	v_max_f32_e32 v156, 0xda24260, v156
	v_max_f32_e32 v160, 0xda24260, v144
	v_max_f32_e32 v157, 0xda24260, v157
	v_max_f32_e32 v145, 0xda24260, v145
	v_max_f32_e32 v158, 0xda24260, v158
	v_max_f32_e32 v161, 0xda24260, v154
	v_max_f32_e32 v159, 0xda24260, v159
	v_max_f32_e32 v155, 0xda24260, v155
	v_rcp_f32_e32 v144, v156
	v_rcp_f32_e32 v154, v157
	v_rcp_f32_e32 v156, v158
	v_rcp_f32_e32 v158, v159
	v_rcp_f32_e32 v159, v155
	v_rcp_f32_e32 v157, v161
	v_rcp_f32_e32 v155, v145
	v_rcp_f32_e32 v145, v160
	v_pk_mul_f32 v[150:151], v[158:159], v[150:151]
	v_pk_mul_f32 v[146:147], v[156:157], v[146:147]
	v_pk_mul_f32 v[152:153], v[154:155], v[152:153]
	v_pk_mul_f32 v[148:149], v[144:145], v[148:149]
